# hand-written epilogues for the sum-of-squares GEMMs (atomics first), the plain gate-lora GEMM and the sigmoid lora GEMM
# speedup vs baseline: 1.0790x; 1.0136x over previous
;     __device__ __forceinline__ void operator()(const f32x4 (&acc)[2][2][4][2], const Unit& u, int wr, int wc, int fr, int fq) const {
;     ...
;         EpiP P; build_epi(a, gl, P);
;         const int colbase = u.pn * BM + wc * 32 + 8 * fq;
;         const int grp = u.pn >> 1;
;         const float* bias = grp == 0 ? P.b0 : (grp == 1 ? P.b1 : (grp == 2 ? P.b2 : P.b3));
; #pragma unroll
;         for (int ai = 0; ai < 2; ++ai)
; #pragma unroll
;             for (int m = 0; m < 4; ++m) {
;                 const int row = u.pm * BM + ai * HALF + wr * 64 + m * 16 + fr;
;                 const float rsc = P.rowscale ? P.scal * P.rowscale[row] : P.scal;
;                 float ss = 0.f;
; #pragma unroll
;                 for (int bj = 0; bj < 2; ++bj) {
;                     const int col = colbase + bj * HALF;
;                     f32x4 v0 = acc[ai][bj][m][0] * rsc, v1 = acc[ai][bj][m][1] * rsc;
;                     if (P.colscale) { const f32x4 c0 = *(const f32x4*)(P.colscale + col), c1 = *(const f32x4*)(P.colscale + col + 4); v0 = v0 * c0; v1 = v1 * c1; }
;                     if (P.act == 1) {
.LBB0_515:
	s_waitcnt lgkmcnt(0)
	s_cmp_eq_u64 s[16:17], 0
	s_cbranch_scc1 .Lfs_test
	s_cmp_lg_u64 s[18:19], 0
	s_cbranch_scc1 .Lfe_generic
	s_cmp_lg_u64 s[20:21], 0
	s_cbranch_scc1 .Lfe_generic
	s_cmp_lg_u64 s[54:55], 0
	s_cbranch_scc1 .Lfe_generic
	s_cmp_lg_u32 s45, 0
	s_cbranch_scc0 .Lfe_fast
	s_branch .Lfe_generic
.Lfs_test:
	s_cmp_lg_u64 s[18:19], 0
	s_cbranch_scc1 .Lfe_generic
	s_cmp_lg_u64 s[20:21], 0
	s_cbranch_scc1 .Lfa_test
	s_cmp_lg_u64 s[26:27], 0
	s_cbranch_scc1 .Lfe_generic
	s_cmp_eq_u64 s[54:55], 0
	s_cbranch_scc1 .Lfp_test
	s_cmp_lg_u32 s44, 1.0
	s_cbranch_scc1 .Lfe_generic
	s_cmp_lg_u32 s29, 2.0
	s_cbranch_scc0 .Lfs_fast
	s_branch .Lfe_generic
.Lfp_test:
	s_cmp_lg_u32 s45, 0
	s_cbranch_scc0 .Lfe_plain
	s_branch .Lfe_generic
.Lfa_test:
	s_cmp_lg_u64 s[26:27], 0
	s_cbranch_scc1 .Lfe_generic
	s_cmp_lg_u64 s[54:55], 0
	s_cbranch_scc1 .Lfe_generic
	s_cmp_lg_u32 s44, 1.0
	s_cbranch_scc1 .Lfe_generic
	s_cmp_lg_u32 s29, 2.0
	s_cbranch_scc1 .Lfe_generic
	s_cmp_lg_u32 s45, 0
	s_cbranch_scc0 .Lfa_fast

; __device__ __forceinline__ float sigmoidf_(float z) { return __builtin_amdgcn_rcpf(1.0f + __expf(-z)); }
;     __device__ __forceinline__ void operator()(const f32x4 (&acc)[2][2][4][2], const Unit& u, int wr, int wc, int fr, int fq) const {
;     ...
;                 const int row = u.pm * BM + ai * HALF + wr * 64 + m * 16 + fr;
;                 const float rsc = P.rowscale ? P.scal * P.rowscale[row] : P.scal;
;                 float ss = 0.f;
; #pragma unroll
;                 for (int bj = 0; bj < 2; ++bj) {
;                     const int col = colbase + bj * HALF;
;                     f32x4 v0 = acc[ai][bj][m][0] * rsc, v1 = acc[ai][bj][m][1] * rsc;
;                     if (P.colscale) { const f32x4 c0 = *(const f32x4*)(P.colscale + col), c1 = *(const f32x4*)(P.colscale + col + 4); v0 = v0 * c0; v1 = v1 * c1; }
;                     if (P.act == 1) {
; #pragma unroll
;                         for (int j = 0; j < 4; ++j) { const float a0 = v0[j] > 0.f ? v0[j] : 0.f, a1 = v1[j] > 0.f ? v1[j] : 0.f; v0[j] = a0 * a0; v1[j] = a1 * a1; }
;                     }
;                     bf16_t* dst = (row < P.split ? P.Olo : P.O) + (size_t)row * P.ldc + col;
;                     if (P.act == 2) {
;                         if (grp < 4) {
;                             const int bc = col - grp * 512;
;                             const f32x4 c0 = *(const f32x4*)(bias + bc), c1 = *(const f32x4*)(bias + bc + 4);
;                             const float mul = grp < 2 ? -0.60653066f : 1.0f;
; #pragma unroll
;                             for (int j = 0; j < 4; ++j) { v0[j] = mul * sigmoidf_(v0[j] + c0[j]); v1[j] = mul * sigmoidf_(v1[j] + c1[j]); }
;                         } else dst = P.O2 + (size_t)row * 512 + (col - 2048);
;                     }
;                     if (P.ssq) ss += (v0[0] * v0[0] + v0[1] * v0[1]) + (v0[2] * v0[2] + v0[3] * v0[3]) + (v1[0] * v1[0] + v1[1] * v1[1]) + (v1[2] * v1[2] + v1[3] * v1[3]);
;                     if (col < P.ncols) { u32x4 w; w.x = pk2(v0[0], v0[1]); w.y = pk2(v0[2], v0[3]); w.z = pk2(v1[0], v1[1]); w.w = pk2(v1[2], v1[3]);
;                         if (P.ldc >= 3504) __builtin_nontemporal_store(w, (u32x4*)dst); else *(u32x4*)dst = w; }
;                 }
;                 if (P.ssq) { ss += __shfl_xor(ss, 16); ss += __shfl_xor(ss, 32); if (fq == 0) atomicAdd(P.ssq + row, ss); }
.Lfs_fast:
	v_lshl_add_u32 v144, s70, 8, v190
	v_ashrrev_i32_e32 v145, 31, v144
	v_lshl_or_b32 v146, s7, 8, v192
	v_pk_mul_f32 v[210:211], v[124:125], v[124:125]
	v_pk_fma_f32 v[210:211], v[126:127], v[126:127], v[210:211]
	v_pk_fma_f32 v[210:211], v[128:129], v[128:129], v[210:211]
	v_pk_fma_f32 v[210:211], v[130:131], v[130:131], v[210:211]
	v_pk_fma_f32 v[210:211], v[116:117], v[116:117], v[210:211]
	v_pk_fma_f32 v[210:211], v[118:119], v[118:119], v[210:211]
	v_pk_fma_f32 v[210:211], v[120:121], v[120:121], v[210:211]
	v_pk_fma_f32 v[210:211], v[122:123], v[122:123], v[210:211]
	v_add_f32_e32 v202, v210, v211
	v_pk_mul_f32 v[212:213], v[108:109], v[108:109]
	v_pk_fma_f32 v[212:213], v[110:111], v[110:111], v[212:213]
	v_pk_fma_f32 v[212:213], v[112:113], v[112:113], v[212:213]
	v_pk_fma_f32 v[212:213], v[114:115], v[114:115], v[212:213]
	v_pk_fma_f32 v[212:213], v[100:101], v[100:101], v[212:213]
	v_pk_fma_f32 v[212:213], v[102:103], v[102:103], v[212:213]
	v_pk_fma_f32 v[212:213], v[104:105], v[104:105], v[212:213]
	v_pk_fma_f32 v[212:213], v[106:107], v[106:107], v[212:213]
	v_add_f32_e32 v203, v212, v213
	v_pk_mul_f32 v[214:215], v[92:93], v[92:93]
	v_pk_fma_f32 v[214:215], v[94:95], v[94:95], v[214:215]
	v_pk_fma_f32 v[214:215], v[96:97], v[96:97], v[214:215]
	v_pk_fma_f32 v[214:215], v[98:99], v[98:99], v[214:215]
	v_pk_fma_f32 v[214:215], v[84:85], v[84:85], v[214:215]
	v_pk_fma_f32 v[214:215], v[86:87], v[86:87], v[214:215]
	v_pk_fma_f32 v[214:215], v[88:89], v[88:89], v[214:215]
	v_pk_fma_f32 v[214:215], v[90:91], v[90:91], v[214:215]
	v_add_f32_e32 v204, v214, v215
	v_pk_mul_f32 v[216:217], v[76:77], v[76:77]
	v_pk_fma_f32 v[216:217], v[78:79], v[78:79], v[216:217]
	v_pk_fma_f32 v[216:217], v[80:81], v[80:81], v[216:217]
	v_pk_fma_f32 v[216:217], v[82:83], v[82:83], v[216:217]
	v_pk_fma_f32 v[216:217], v[68:69], v[68:69], v[216:217]
	v_pk_fma_f32 v[216:217], v[70:71], v[70:71], v[216:217]
	v_pk_fma_f32 v[216:217], v[72:73], v[72:73], v[216:217]
	v_pk_fma_f32 v[216:217], v[74:75], v[74:75], v[216:217]
	v_add_f32_e32 v205, v216, v217
	v_pk_mul_f32 v[218:219], v[60:61], v[60:61]
	v_pk_fma_f32 v[218:219], v[62:63], v[62:63], v[218:219]
	v_pk_fma_f32 v[218:219], v[64:65], v[64:65], v[218:219]
	v_pk_fma_f32 v[218:219], v[66:67], v[66:67], v[218:219]
	v_pk_fma_f32 v[218:219], v[52:53], v[52:53], v[218:219]
	v_pk_fma_f32 v[218:219], v[54:55], v[54:55], v[218:219]
	v_pk_fma_f32 v[218:219], v[56:57], v[56:57], v[218:219]
	v_pk_fma_f32 v[218:219], v[58:59], v[58:59], v[218:219]
	v_add_f32_e32 v206, v218, v219
	v_pk_mul_f32 v[220:221], v[44:45], v[44:45]
	v_pk_fma_f32 v[220:221], v[46:47], v[46:47], v[220:221]
	v_pk_fma_f32 v[220:221], v[48:49], v[48:49], v[220:221]
	v_pk_fma_f32 v[220:221], v[50:51], v[50:51], v[220:221]
	v_pk_fma_f32 v[220:221], v[36:37], v[36:37], v[220:221]
	v_pk_fma_f32 v[220:221], v[38:39], v[38:39], v[220:221]
	v_pk_fma_f32 v[220:221], v[40:41], v[40:41], v[220:221]
	v_pk_fma_f32 v[220:221], v[42:43], v[42:43], v[220:221]
	v_add_f32_e32 v207, v220, v221
	v_pk_mul_f32 v[222:223], v[28:29], v[28:29]
	v_pk_fma_f32 v[222:223], v[30:31], v[30:31], v[222:223]
	v_pk_fma_f32 v[222:223], v[32:33], v[32:33], v[222:223]
	v_pk_fma_f32 v[222:223], v[34:35], v[34:35], v[222:223]
	v_pk_fma_f32 v[222:223], v[20:21], v[20:21], v[222:223]
	v_pk_fma_f32 v[222:223], v[22:23], v[22:23], v[222:223]
	v_pk_fma_f32 v[222:223], v[24:25], v[24:25], v[222:223]
	v_pk_fma_f32 v[222:223], v[26:27], v[26:27], v[222:223]
	v_add_f32_e32 v208, v222, v223
	v_pk_mul_f32 v[224:225], v[8:9], v[8:9]
	v_pk_fma_f32 v[224:225], v[10:11], v[10:11], v[224:225]
	v_pk_fma_f32 v[224:225], v[12:13], v[12:13], v[224:225]
	v_pk_fma_f32 v[224:225], v[14:15], v[14:15], v[224:225]
	v_pk_fma_f32 v[224:225], v[0:1], v[0:1], v[224:225]
	v_pk_fma_f32 v[224:225], v[2:3], v[2:3], v[224:225]
	v_pk_fma_f32 v[224:225], v[4:5], v[4:5], v[224:225]
	v_pk_fma_f32 v[224:225], v[6:7], v[6:7], v[224:225]
	v_add_f32_e32 v209, v224, v225
	v_xor_b32_e32 v147, 16, v164
	v_xor_b32_e32 v148, 32, v164
	v_lshlrev_b32_e32 v147, 2, v147
	v_lshlrev_b32_e32 v148, 2, v148
	ds_bpermute_b32 v210, v147, v202
	ds_bpermute_b32 v211, v147, v203
	ds_bpermute_b32 v212, v147, v204
	ds_bpermute_b32 v213, v147, v205
	ds_bpermute_b32 v214, v147, v206
	ds_bpermute_b32 v215, v147, v207
	ds_bpermute_b32 v216, v147, v208
	ds_bpermute_b32 v217, v147, v209
	v_lshl_add_u64 v[150:151], v[144:145], 2, s[54:55]
	v_mul_lo_u32 v152, v144, s58
	v_add_lshl_u32 v152, v152, v146, 1
	s_waitcnt lgkmcnt(0)
	v_add_f32_e32 v202, v202, v210
	v_add_f32_e32 v203, v203, v211
	v_add_f32_e32 v204, v204, v212
	v_add_f32_e32 v205, v205, v213
	v_add_f32_e32 v206, v206, v214
	v_add_f32_e32 v207, v207, v215
	v_add_f32_e32 v208, v208, v216
	v_add_f32_e32 v209, v209, v217
	ds_bpermute_b32 v210, v148, v202
	ds_bpermute_b32 v211, v148, v203
	ds_bpermute_b32 v212, v148, v204
	ds_bpermute_b32 v213, v148, v205
	ds_bpermute_b32 v214, v148, v206
	ds_bpermute_b32 v215, v148, v207
	ds_bpermute_b32 v216, v148, v208
	ds_bpermute_b32 v217, v148, v209
	s_lshl_b32 s12, s58, 5
	s_mul_i32 s13, s58, 0xa0
	s_lshl_b32 s14, s70, 8
	s_cmp_lt_i32 s14, s45
	s_cselect_b32 s16, s64, s56
	s_cselect_b32 s17, s65, s57
	s_waitcnt lgkmcnt(0)
; __device__ __forceinline__ unsigned pk2(float lo, float hi) { const f32x2 v = {lo, hi}; return __builtin_bit_cast(unsigned, __builtin_convertvector(v, bf16x2_t)); }
; __device__ __forceinline__ float sigmoidf_(float z) { return __builtin_amdgcn_rcpf(1.0f + __expf(-z)); }
;     __device__ __forceinline__ void operator()(const f32x4 (&acc)[2][2][4][2], const Unit& u, int wr, int wc, int fr, int fq) const {
;     ...
;                             const int bc = col - grp * 512;
;                             const f32x4 c0 = *(const f32x4*)(bias + bc), c1 = *(const f32x4*)(bias + bc + 4);
;                             const float mul = grp < 2 ? -0.60653066f : 1.0f;
; #pragma unroll
;                             for (int j = 0; j < 4; ++j) { v0[j] = mul * sigmoidf_(v0[j] + c0[j]); v1[j] = mul * sigmoidf_(v1[j] + c1[j]); }
;                         } else dst = P.O2 + (size_t)row * 512 + (col - 2048);
;                     }
;                     if (P.ssq) ss += (v0[0] * v0[0] + v0[1] * v0[1]) + (v0[2] * v0[2] + v0[3] * v0[3]) + (v1[0] * v1[0] + v1[1] * v1[1]) + (v1[2] * v1[2] + v1[3] * v1[3]);
;                     if (col < P.ncols) { u32x4 w; w.x = pk2(v0[0], v0[1]); w.y = pk2(v0[2], v0[3]); w.z = pk2(v1[0], v1[1]); w.w = pk2(v1[2], v1[3]);
;                         if (P.ldc >= 3504) __builtin_nontemporal_store(w, (u32x4*)dst); else *(u32x4*)dst = w; }
;                 }
;                 if (P.ssq) { ss += __shfl_xor(ss, 16); ss += __shfl_xor(ss, 32); if (fq == 0) atomicAdd(P.ssq + row, ss); }
	v_add_f32_e32 v202, v202, v210
	v_add_f32_e32 v203, v203, v211
	v_add_f32_e32 v204, v204, v212
	v_add_f32_e32 v205, v205, v213
	v_add_f32_e32 v206, v206, v214
	v_add_f32_e32 v207, v207, v215
	v_add_f32_e32 v208, v208, v216
	v_add_f32_e32 v209, v209, v217
	s_mov_b64 s[14:15], exec
	s_and_b64 exec, s[14:15], s[8:9]
	global_atomic_add_f32 v[150:151], v202, off
	global_atomic_add_f32 v[150:151], v203, off offset:64
	global_atomic_add_f32 v[150:151], v204, off offset:128
	global_atomic_add_f32 v[150:151], v205, off offset:192
	global_atomic_add_f32 v[150:151], v206, off offset:512
	global_atomic_add_f32 v[150:151], v207, off offset:576
	global_atomic_add_f32 v[150:151], v208, off offset:640
	global_atomic_add_f32 v[150:151], v209, off offset:704
	s_mov_b64 exec, s[14:15]
	v_cvt_pk_bf16_f32 v128, v128, v129
	v_cvt_pk_bf16_f32 v129, v130, v131
	v_cvt_pk_bf16_f32 v130, v124, v125
	v_cvt_pk_bf16_f32 v131, v126, v127
	v_cvt_pk_bf16_f32 v120, v120, v121
	v_cvt_pk_bf16_f32 v121, v122, v123
	v_cvt_pk_bf16_f32 v122, v116, v117
	v_cvt_pk_bf16_f32 v123, v118, v119
	global_store_dwordx4 v152, v[128:131], s[16:17]
	global_store_dwordx4 v152, v[120:123], s[16:17] offset:256
	v_add_u32_e32 v152, s12, v152
	v_cvt_pk_bf16_f32 v112, v112, v113
	v_cvt_pk_bf16_f32 v113, v114, v115
	v_cvt_pk_bf16_f32 v114, v108, v109
	v_cvt_pk_bf16_f32 v115, v110, v111
	v_cvt_pk_bf16_f32 v104, v104, v105
	v_cvt_pk_bf16_f32 v105, v106, v107
	v_cvt_pk_bf16_f32 v106, v100, v101
	v_cvt_pk_bf16_f32 v107, v102, v103
	global_store_dwordx4 v152, v[112:115], s[16:17]
	global_store_dwordx4 v152, v[104:107], s[16:17] offset:256
	v_add_u32_e32 v152, s12, v152
	v_cvt_pk_bf16_f32 v96, v96, v97
	v_cvt_pk_bf16_f32 v97, v98, v99
	v_cvt_pk_bf16_f32 v98, v92, v93
	v_cvt_pk_bf16_f32 v99, v94, v95
	v_cvt_pk_bf16_f32 v88, v88, v89
	v_cvt_pk_bf16_f32 v89, v90, v91
	v_cvt_pk_bf16_f32 v90, v84, v85
	v_cvt_pk_bf16_f32 v91, v86, v87
	global_store_dwordx4 v152, v[96:99], s[16:17]
	global_store_dwordx4 v152, v[88:91], s[16:17] offset:256
	v_add_u32_e32 v152, s12, v152
	v_cvt_pk_bf16_f32 v80, v80, v81
	v_cvt_pk_bf16_f32 v81, v82, v83
	v_cvt_pk_bf16_f32 v82, v76, v77
	v_cvt_pk_bf16_f32 v83, v78, v79
	v_cvt_pk_bf16_f32 v72, v72, v73
	v_cvt_pk_bf16_f32 v73, v74, v75
	v_cvt_pk_bf16_f32 v74, v68, v69
	v_cvt_pk_bf16_f32 v75, v70, v71
	global_store_dwordx4 v152, v[80:83], s[16:17]
	global_store_dwordx4 v152, v[72:75], s[16:17] offset:256
	v_add_u32_e32 v152, s13, v152
	v_cvt_pk_bf16_f32 v64, v64, v65
	v_cvt_pk_bf16_f32 v65, v66, v67
	v_cvt_pk_bf16_f32 v66, v60, v61
	v_cvt_pk_bf16_f32 v67, v62, v63
	v_cvt_pk_bf16_f32 v56, v56, v57
	v_cvt_pk_bf16_f32 v57, v58, v59
	v_cvt_pk_bf16_f32 v58, v52, v53
	v_cvt_pk_bf16_f32 v59, v54, v55
	global_store_dwordx4 v152, v[64:67], s[16:17]
	global_store_dwordx4 v152, v[56:59], s[16:17] offset:256
	v_add_u32_e32 v152, s12, v152
	v_cvt_pk_bf16_f32 v48, v48, v49
	v_cvt_pk_bf16_f32 v49, v50, v51
	v_cvt_pk_bf16_f32 v50, v44, v45
	v_cvt_pk_bf16_f32 v51, v46, v47
	v_cvt_pk_bf16_f32 v40, v40, v41
	v_cvt_pk_bf16_f32 v41, v42, v43
	v_cvt_pk_bf16_f32 v42, v36, v37
	v_cvt_pk_bf16_f32 v43, v38, v39
	global_store_dwordx4 v152, v[48:51], s[16:17]
	global_store_dwordx4 v152, v[40:43], s[16:17] offset:256
	v_add_u32_e32 v152, s12, v152
	v_cvt_pk_bf16_f32 v32, v32, v33
	v_cvt_pk_bf16_f32 v33, v34, v35
	v_cvt_pk_bf16_f32 v34, v28, v29
	v_cvt_pk_bf16_f32 v35, v30, v31
	v_cvt_pk_bf16_f32 v24, v24, v25
	v_cvt_pk_bf16_f32 v25, v26, v27
	v_cvt_pk_bf16_f32 v26, v20, v21
	v_cvt_pk_bf16_f32 v27, v22, v23
	global_store_dwordx4 v152, v[32:35], s[16:17]
	global_store_dwordx4 v152, v[24:27], s[16:17] offset:256
	v_add_u32_e32 v152, s12, v152
	v_cvt_pk_bf16_f32 v12, v12, v13
	v_cvt_pk_bf16_f32 v13, v14, v15
	v_cvt_pk_bf16_f32 v14, v8, v9
	v_cvt_pk_bf16_f32 v15, v10, v11
	v_cvt_pk_bf16_f32 v4, v4, v5
	v_cvt_pk_bf16_f32 v5, v6, v7
	v_cvt_pk_bf16_f32 v6, v0, v1
	v_cvt_pk_bf16_f32 v7, v2, v3
	global_store_dwordx4 v152, v[12:15], s[16:17]
	global_store_dwordx4 v152, v[4:7], s[16:17] offset:256
	s_branch .LBB0_467
.Lfa_fast:
	s_ashr_i32 s14, s7, 1
	s_cmp_gt_i32 s14, 3
	s_cbranch_scc1 .Lfe_generic
	v_lshl_add_u32 v144, s70, 8, v190
	v_lshl_or_b32 v146, s7, 8, v192
	s_cmp_eq_u32 s14, 2
	s_cselect_b32 s13, s63, s69
	s_cselect_b32 s12, s62, s68
	s_cmp_eq_u32 s14, 1
	s_cselect_b32 s12, s24, s12
	s_cselect_b32 s13, s25, s13
	s_cmp_eq_u32 s14, 0
	s_cselect_b32 s12, s22, s12
	s_cselect_b32 s13, s23, s13
	s_lshl_b32 s15, s14, 9
	v_subrev_u32_e32 v147, s15, v146
	v_lshlrev_b32_e32 v147, 2, v147
	global_load_dwordx4 v[210:213], v147, s[12:13]
	global_load_dwordx4 v[214:217], v147, s[12:13] offset:16
	global_load_dwordx4 v[218:221], v147, s[12:13] offset:512
	global_load_dwordx4 v[222:225], v147, s[12:13] offset:528
	s_cmp_lt_i32 s14, 2
	s_cselect_b32 s16, 0xbf1b4598, 1.0
	v_mov_b32_e32 v158, s16
	v_mul_lo_u32 v150, v144, s58
	v_add_lshl_u32 v150, v150, v146, 1
	s_lshl_b32 s12, s58, 5
	s_mul_i32 s13, s58, 0xa0
	v_add_u32_e32 v151, s12, v150
	v_add_u32_e32 v152, s12, v151
	v_add_u32_e32 v153, s12, v152
	v_add_u32_e32 v154, s13, v153
	v_add_u32_e32 v155, s12, v154
	v_add_u32_e32 v156, s12, v155
	v_add_u32_e32 v157, s12, v156
	s_waitcnt vmcnt(0)
; __device__ __forceinline__ unsigned pk2(float lo, float hi) { const f32x2 v = {lo, hi}; return __builtin_bit_cast(unsigned, __builtin_convertvector(v, bf16x2_t)); }
; __device__ __forceinline__ float sigmoidf_(float z) { return __builtin_amdgcn_rcpf(1.0f + __expf(-z)); }
;     __device__ __forceinline__ void operator()(const f32x4 (&acc)[2][2][4][2], const Unit& u, int wr, int wc, int fr, int fq) const {
;     ...
;                     if (P.act == 2) {
;                         if (grp < 4) {
;                             const int bc = col - grp * 512;
;                             const f32x4 c0 = *(const f32x4*)(bias + bc), c1 = *(const f32x4*)(bias + bc + 4);
;                             const float mul = grp < 2 ? -0.60653066f : 1.0f;
; #pragma unroll
;                             for (int j = 0; j < 4; ++j) { v0[j] = mul * sigmoidf_(v0[j] + c0[j]); v1[j] = mul * sigmoidf_(v1[j] + c1[j]); }
;                         } else dst = P.O2 + (size_t)row * 512 + (col - 2048);
;                     }
;                     if (P.ssq) ss += (v0[0] * v0[0] + v0[1] * v0[1]) + (v0[2] * v0[2] + v0[3] * v0[3]) + (v1[0] * v1[0] + v1[1] * v1[1]) + (v1[2] * v1[2] + v1[3] * v1[3]);
;                     if (col < P.ncols) { u32x4 w; w.x = pk2(v0[0], v0[1]); w.y = pk2(v0[2], v0[3]); w.z = pk2(v1[0], v1[1]); w.w = pk2(v1[2], v1[3]);
;                         if (P.ldc >= 3504) __builtin_nontemporal_store(w, (u32x4*)dst); else *(u32x4*)dst = w; }
	v_add_f32_e32 v128, v128, v210
	v_add_f32_e32 v129, v129, v211
	v_add_f32_e32 v130, v130, v212
	v_add_f32_e32 v131, v131, v213
	v_add_f32_e32 v124, v124, v214
	v_add_f32_e32 v125, v125, v215
	v_add_f32_e32 v126, v126, v216
	v_add_f32_e32 v127, v127, v217
	v_add_f32_e32 v120, v120, v218
	v_add_f32_e32 v121, v121, v219
	v_add_f32_e32 v122, v122, v220
	v_add_f32_e32 v123, v123, v221
	v_add_f32_e32 v116, v116, v222
	v_add_f32_e32 v117, v117, v223
	v_add_f32_e32 v118, v118, v224
	v_add_f32_e32 v119, v119, v225
	v_mul_f32_e32 v128, 0xbfb8aa3b, v128
	v_mul_f32_e32 v129, 0xbfb8aa3b, v129
	v_mul_f32_e32 v130, 0xbfb8aa3b, v130
	v_mul_f32_e32 v131, 0xbfb8aa3b, v131
	v_mul_f32_e32 v124, 0xbfb8aa3b, v124
	v_mul_f32_e32 v125, 0xbfb8aa3b, v125
	v_mul_f32_e32 v126, 0xbfb8aa3b, v126
	v_mul_f32_e32 v127, 0xbfb8aa3b, v127
	v_mul_f32_e32 v120, 0xbfb8aa3b, v120
	v_mul_f32_e32 v121, 0xbfb8aa3b, v121
	v_mul_f32_e32 v122, 0xbfb8aa3b, v122
	v_mul_f32_e32 v123, 0xbfb8aa3b, v123
	v_mul_f32_e32 v116, 0xbfb8aa3b, v116
	v_mul_f32_e32 v117, 0xbfb8aa3b, v117
	v_mul_f32_e32 v118, 0xbfb8aa3b, v118
	v_mul_f32_e32 v119, 0xbfb8aa3b, v119
	v_exp_f32_e32 v128, v128
	v_exp_f32_e32 v129, v129
	v_exp_f32_e32 v130, v130
	v_exp_f32_e32 v131, v131
	v_exp_f32_e32 v124, v124
	v_exp_f32_e32 v125, v125
	v_exp_f32_e32 v126, v126
	v_exp_f32_e32 v127, v127
	v_exp_f32_e32 v120, v120
	v_exp_f32_e32 v121, v121
	v_exp_f32_e32 v122, v122
	v_exp_f32_e32 v123, v123
	v_exp_f32_e32 v116, v116
	v_exp_f32_e32 v117, v117
	v_exp_f32_e32 v118, v118
	v_exp_f32_e32 v119, v119
	v_add_f32_e32 v128, 1.0, v128
	v_add_f32_e32 v129, 1.0, v129
	v_add_f32_e32 v130, 1.0, v130
	v_add_f32_e32 v131, 1.0, v131
	v_add_f32_e32 v124, 1.0, v124
	v_add_f32_e32 v125, 1.0, v125
	v_add_f32_e32 v126, 1.0, v126
	v_add_f32_e32 v127, 1.0, v127
	v_add_f32_e32 v120, 1.0, v120
	v_add_f32_e32 v121, 1.0, v121
	v_add_f32_e32 v122, 1.0, v122
	v_add_f32_e32 v123, 1.0, v123
	v_add_f32_e32 v116, 1.0, v116
	v_add_f32_e32 v117, 1.0, v117
	v_add_f32_e32 v118, 1.0, v118
	v_add_f32_e32 v119, 1.0, v119
	v_rcp_f32_e32 v128, v128
	v_rcp_f32_e32 v129, v129
	v_rcp_f32_e32 v130, v130
	v_rcp_f32_e32 v131, v131
	v_rcp_f32_e32 v124, v124
	v_rcp_f32_e32 v125, v125
	v_rcp_f32_e32 v126, v126
	v_rcp_f32_e32 v127, v127
	v_rcp_f32_e32 v120, v120
	v_rcp_f32_e32 v121, v121
	v_rcp_f32_e32 v122, v122
	v_rcp_f32_e32 v123, v123
	v_rcp_f32_e32 v116, v116
	v_rcp_f32_e32 v117, v117
	v_rcp_f32_e32 v118, v118
	v_rcp_f32_e32 v119, v119
	v_pk_mul_f32 v[124:125], v[158:159], v[124:125] op_sel_hi:[0,1]
	v_pk_mul_f32 v[126:127], v[158:159], v[126:127] op_sel_hi:[0,1]
	v_pk_mul_f32 v[128:129], v[158:159], v[128:129] op_sel_hi:[0,1]
	v_pk_mul_f32 v[130:131], v[158:159], v[130:131] op_sel_hi:[0,1]
	v_pk_mul_f32 v[116:117], v[158:159], v[116:117] op_sel_hi:[0,1]
	v_pk_mul_f32 v[118:119], v[158:159], v[118:119] op_sel_hi:[0,1]
	v_pk_mul_f32 v[120:121], v[158:159], v[120:121] op_sel_hi:[0,1]
	v_pk_mul_f32 v[122:123], v[158:159], v[122:123] op_sel_hi:[0,1]
	v_cvt_pk_bf16_f32 v128, v128, v129
	v_cvt_pk_bf16_f32 v129, v130, v131
	v_cvt_pk_bf16_f32 v130, v124, v125
	v_cvt_pk_bf16_f32 v131, v126, v127
	v_cvt_pk_bf16_f32 v120, v120, v121
	v_cvt_pk_bf16_f32 v121, v122, v123
	v_cvt_pk_bf16_f32 v122, v116, v117
	v_cvt_pk_bf16_f32 v123, v118, v119
	global_store_dwordx4 v150, v[128:131], s[56:57]
	global_store_dwordx4 v150, v[120:123], s[56:57] offset:256
	v_add_f32_e32 v112, v112, v210
	v_add_f32_e32 v113, v113, v211
	v_add_f32_e32 v114, v114, v212
	v_add_f32_e32 v115, v115, v213
	v_add_f32_e32 v108, v108, v214
	v_add_f32_e32 v109, v109, v215
	v_add_f32_e32 v110, v110, v216
	v_add_f32_e32 v111, v111, v217
	v_add_f32_e32 v104, v104, v218
	v_add_f32_e32 v105, v105, v219
	v_add_f32_e32 v106, v106, v220
	v_add_f32_e32 v107, v107, v221
	v_add_f32_e32 v100, v100, v222
	v_add_f32_e32 v101, v101, v223
	v_add_f32_e32 v102, v102, v224
	v_add_f32_e32 v103, v103, v225
	v_mul_f32_e32 v112, 0xbfb8aa3b, v112
	v_mul_f32_e32 v113, 0xbfb8aa3b, v113
	v_mul_f32_e32 v114, 0xbfb8aa3b, v114
	v_mul_f32_e32 v115, 0xbfb8aa3b, v115
	v_mul_f32_e32 v108, 0xbfb8aa3b, v108
	v_mul_f32_e32 v109, 0xbfb8aa3b, v109
	v_mul_f32_e32 v110, 0xbfb8aa3b, v110
	v_mul_f32_e32 v111, 0xbfb8aa3b, v111
	v_mul_f32_e32 v104, 0xbfb8aa3b, v104
	v_mul_f32_e32 v105, 0xbfb8aa3b, v105
	v_mul_f32_e32 v106, 0xbfb8aa3b, v106
	v_mul_f32_e32 v107, 0xbfb8aa3b, v107
	v_mul_f32_e32 v100, 0xbfb8aa3b, v100
	v_mul_f32_e32 v101, 0xbfb8aa3b, v101
	v_mul_f32_e32 v102, 0xbfb8aa3b, v102
	v_mul_f32_e32 v103, 0xbfb8aa3b, v103
	v_exp_f32_e32 v112, v112
	v_exp_f32_e32 v113, v113
	v_exp_f32_e32 v114, v114
	v_exp_f32_e32 v115, v115
	v_exp_f32_e32 v108, v108
	v_exp_f32_e32 v109, v109
	v_exp_f32_e32 v110, v110
	v_exp_f32_e32 v111, v111
	v_exp_f32_e32 v104, v104
	v_exp_f32_e32 v105, v105
	v_exp_f32_e32 v106, v106
	v_exp_f32_e32 v107, v107
	v_exp_f32_e32 v100, v100
	v_exp_f32_e32 v101, v101
	v_exp_f32_e32 v102, v102
	v_exp_f32_e32 v103, v103
	v_add_f32_e32 v112, 1.0, v112
	v_add_f32_e32 v113, 1.0, v113
	v_add_f32_e32 v114, 1.0, v114
	v_add_f32_e32 v115, 1.0, v115
	v_add_f32_e32 v108, 1.0, v108
	v_add_f32_e32 v109, 1.0, v109
	v_add_f32_e32 v110, 1.0, v110
	v_add_f32_e32 v111, 1.0, v111
	v_add_f32_e32 v104, 1.0, v104
	v_add_f32_e32 v105, 1.0, v105
	v_add_f32_e32 v106, 1.0, v106
	v_add_f32_e32 v107, 1.0, v107
	v_add_f32_e32 v100, 1.0, v100
	v_add_f32_e32 v101, 1.0, v101
	v_add_f32_e32 v102, 1.0, v102
	v_add_f32_e32 v103, 1.0, v103
	v_rcp_f32_e32 v112, v112
	v_rcp_f32_e32 v113, v113
	v_rcp_f32_e32 v114, v114
	v_rcp_f32_e32 v115, v115
	v_rcp_f32_e32 v108, v108
	v_rcp_f32_e32 v109, v109
	v_rcp_f32_e32 v110, v110
	v_rcp_f32_e32 v111, v111
	v_rcp_f32_e32 v104, v104
; __device__ __forceinline__ unsigned pk2(float lo, float hi) { const f32x2 v = {lo, hi}; return __builtin_bit_cast(unsigned, __builtin_convertvector(v, bf16x2_t)); }
; __device__ __forceinline__ float sigmoidf_(float z) { return __builtin_amdgcn_rcpf(1.0f + __expf(-z)); }
;     __device__ __forceinline__ void operator()(const f32x4 (&acc)[2][2][4][2], const Unit& u, int wr, int wc, int fr, int fq) const {
;     ...
;                     if (P.act == 2) {
;                         if (grp < 4) {
;                             const int bc = col - grp * 512;
;                             const f32x4 c0 = *(const f32x4*)(bias + bc), c1 = *(const f32x4*)(bias + bc + 4);
;                             const float mul = grp < 2 ? -0.60653066f : 1.0f;
; #pragma unroll
;                             for (int j = 0; j < 4; ++j) { v0[j] = mul * sigmoidf_(v0[j] + c0[j]); v1[j] = mul * sigmoidf_(v1[j] + c1[j]); }
;                         } else dst = P.O2 + (size_t)row * 512 + (col - 2048);
;                     }
;                     if (P.ssq) ss += (v0[0] * v0[0] + v0[1] * v0[1]) + (v0[2] * v0[2] + v0[3] * v0[3]) + (v1[0] * v1[0] + v1[1] * v1[1]) + (v1[2] * v1[2] + v1[3] * v1[3]);
;                     if (col < P.ncols) { u32x4 w; w.x = pk2(v0[0], v0[1]); w.y = pk2(v0[2], v0[3]); w.z = pk2(v1[0], v1[1]); w.w = pk2(v1[2], v1[3]);
;                         if (P.ldc >= 3504) __builtin_nontemporal_store(w, (u32x4*)dst); else *(u32x4*)dst = w; }
	v_rcp_f32_e32 v105, v105
	v_rcp_f32_e32 v106, v106
	v_rcp_f32_e32 v107, v107
	v_rcp_f32_e32 v100, v100
	v_rcp_f32_e32 v101, v101
	v_rcp_f32_e32 v102, v102
	v_rcp_f32_e32 v103, v103
	v_pk_mul_f32 v[108:109], v[158:159], v[108:109] op_sel_hi:[0,1]
	v_pk_mul_f32 v[110:111], v[158:159], v[110:111] op_sel_hi:[0,1]
	v_pk_mul_f32 v[112:113], v[158:159], v[112:113] op_sel_hi:[0,1]
	v_pk_mul_f32 v[114:115], v[158:159], v[114:115] op_sel_hi:[0,1]
	v_pk_mul_f32 v[100:101], v[158:159], v[100:101] op_sel_hi:[0,1]
	v_pk_mul_f32 v[102:103], v[158:159], v[102:103] op_sel_hi:[0,1]
	v_pk_mul_f32 v[104:105], v[158:159], v[104:105] op_sel_hi:[0,1]
	v_pk_mul_f32 v[106:107], v[158:159], v[106:107] op_sel_hi:[0,1]
	v_cvt_pk_bf16_f32 v112, v112, v113
	v_cvt_pk_bf16_f32 v113, v114, v115
	v_cvt_pk_bf16_f32 v114, v108, v109
	v_cvt_pk_bf16_f32 v115, v110, v111
	v_cvt_pk_bf16_f32 v104, v104, v105
	v_cvt_pk_bf16_f32 v105, v106, v107
	v_cvt_pk_bf16_f32 v106, v100, v101
	v_cvt_pk_bf16_f32 v107, v102, v103
	global_store_dwordx4 v151, v[112:115], s[56:57]
	global_store_dwordx4 v151, v[104:107], s[56:57] offset:256
	v_add_f32_e32 v96, v96, v210
	v_add_f32_e32 v97, v97, v211
	v_add_f32_e32 v98, v98, v212
	v_add_f32_e32 v99, v99, v213
	v_add_f32_e32 v92, v92, v214
	v_add_f32_e32 v93, v93, v215
	v_add_f32_e32 v94, v94, v216
	v_add_f32_e32 v95, v95, v217
	v_add_f32_e32 v88, v88, v218
	v_add_f32_e32 v89, v89, v219
	v_add_f32_e32 v90, v90, v220
	v_add_f32_e32 v91, v91, v221
	v_add_f32_e32 v84, v84, v222
	v_add_f32_e32 v85, v85, v223
	v_add_f32_e32 v86, v86, v224
	v_add_f32_e32 v87, v87, v225
	v_mul_f32_e32 v96, 0xbfb8aa3b, v96
	v_mul_f32_e32 v97, 0xbfb8aa3b, v97
	v_mul_f32_e32 v98, 0xbfb8aa3b, v98
	v_mul_f32_e32 v99, 0xbfb8aa3b, v99
	v_mul_f32_e32 v92, 0xbfb8aa3b, v92
	v_mul_f32_e32 v93, 0xbfb8aa3b, v93
	v_mul_f32_e32 v94, 0xbfb8aa3b, v94
	v_mul_f32_e32 v95, 0xbfb8aa3b, v95
	v_mul_f32_e32 v88, 0xbfb8aa3b, v88
	v_mul_f32_e32 v89, 0xbfb8aa3b, v89
	v_mul_f32_e32 v90, 0xbfb8aa3b, v90
	v_mul_f32_e32 v91, 0xbfb8aa3b, v91
	v_mul_f32_e32 v84, 0xbfb8aa3b, v84
	v_mul_f32_e32 v85, 0xbfb8aa3b, v85
	v_mul_f32_e32 v86, 0xbfb8aa3b, v86
	v_mul_f32_e32 v87, 0xbfb8aa3b, v87
	v_exp_f32_e32 v96, v96
	v_exp_f32_e32 v97, v97
	v_exp_f32_e32 v98, v98
	v_exp_f32_e32 v99, v99
	v_exp_f32_e32 v92, v92
	v_exp_f32_e32 v93, v93
	v_exp_f32_e32 v94, v94
	v_exp_f32_e32 v95, v95
	v_exp_f32_e32 v88, v88
	v_exp_f32_e32 v89, v89
	v_exp_f32_e32 v90, v90
	v_exp_f32_e32 v91, v91
	v_exp_f32_e32 v84, v84
	v_exp_f32_e32 v85, v85
	v_exp_f32_e32 v86, v86
	v_exp_f32_e32 v87, v87
	v_add_f32_e32 v96, 1.0, v96
	v_add_f32_e32 v97, 1.0, v97
	v_add_f32_e32 v98, 1.0, v98
	v_add_f32_e32 v99, 1.0, v99
	v_add_f32_e32 v92, 1.0, v92
	v_add_f32_e32 v93, 1.0, v93
	v_add_f32_e32 v94, 1.0, v94
	v_add_f32_e32 v95, 1.0, v95
	v_add_f32_e32 v88, 1.0, v88
	v_add_f32_e32 v89, 1.0, v89
	v_add_f32_e32 v90, 1.0, v90
	v_add_f32_e32 v91, 1.0, v91
	v_add_f32_e32 v84, 1.0, v84
	v_add_f32_e32 v85, 1.0, v85
	v_add_f32_e32 v86, 1.0, v86
	v_add_f32_e32 v87, 1.0, v87
	v_rcp_f32_e32 v96, v96
	v_rcp_f32_e32 v97, v97
	v_rcp_f32_e32 v98, v98
	v_rcp_f32_e32 v99, v99
	v_rcp_f32_e32 v92, v92
	v_rcp_f32_e32 v93, v93
	v_rcp_f32_e32 v94, v94
	v_rcp_f32_e32 v95, v95
	v_rcp_f32_e32 v88, v88
	v_rcp_f32_e32 v89, v89
	v_rcp_f32_e32 v90, v90
	v_rcp_f32_e32 v91, v91
	v_rcp_f32_e32 v84, v84
	v_rcp_f32_e32 v85, v85
	v_rcp_f32_e32 v86, v86
	v_rcp_f32_e32 v87, v87
	v_pk_mul_f32 v[92:93], v[158:159], v[92:93] op_sel_hi:[0,1]
	v_pk_mul_f32 v[94:95], v[158:159], v[94:95] op_sel_hi:[0,1]
	v_pk_mul_f32 v[96:97], v[158:159], v[96:97] op_sel_hi:[0,1]
	v_pk_mul_f32 v[98:99], v[158:159], v[98:99] op_sel_hi:[0,1]
	v_pk_mul_f32 v[84:85], v[158:159], v[84:85] op_sel_hi:[0,1]
	v_pk_mul_f32 v[86:87], v[158:159], v[86:87] op_sel_hi:[0,1]
	v_pk_mul_f32 v[88:89], v[158:159], v[88:89] op_sel_hi:[0,1]
	v_pk_mul_f32 v[90:91], v[158:159], v[90:91] op_sel_hi:[0,1]
	v_cvt_pk_bf16_f32 v96, v96, v97
	v_cvt_pk_bf16_f32 v97, v98, v99
	v_cvt_pk_bf16_f32 v98, v92, v93
	v_cvt_pk_bf16_f32 v99, v94, v95
	v_cvt_pk_bf16_f32 v88, v88, v89
	v_cvt_pk_bf16_f32 v89, v90, v91
	v_cvt_pk_bf16_f32 v90, v84, v85
	v_cvt_pk_bf16_f32 v91, v86, v87
	global_store_dwordx4 v152, v[96:99], s[56:57]
	global_store_dwordx4 v152, v[88:91], s[56:57] offset:256
	v_add_f32_e32 v80, v80, v210
	v_add_f32_e32 v81, v81, v211
	v_add_f32_e32 v82, v82, v212
	v_add_f32_e32 v83, v83, v213
	v_add_f32_e32 v76, v76, v214
	v_add_f32_e32 v77, v77, v215
	v_add_f32_e32 v78, v78, v216
	v_add_f32_e32 v79, v79, v217
	v_add_f32_e32 v72, v72, v218
	v_add_f32_e32 v73, v73, v219
	v_add_f32_e32 v74, v74, v220
	v_add_f32_e32 v75, v75, v221
	v_add_f32_e32 v68, v68, v222
	v_add_f32_e32 v69, v69, v223
	v_add_f32_e32 v70, v70, v224
	v_add_f32_e32 v71, v71, v225
	v_mul_f32_e32 v80, 0xbfb8aa3b, v80
	v_mul_f32_e32 v81, 0xbfb8aa3b, v81
	v_mul_f32_e32 v82, 0xbfb8aa3b, v82
	v_mul_f32_e32 v83, 0xbfb8aa3b, v83
	v_mul_f32_e32 v76, 0xbfb8aa3b, v76
	v_mul_f32_e32 v77, 0xbfb8aa3b, v77
	v_mul_f32_e32 v78, 0xbfb8aa3b, v78
	v_mul_f32_e32 v79, 0xbfb8aa3b, v79
	v_mul_f32_e32 v72, 0xbfb8aa3b, v72
	v_mul_f32_e32 v73, 0xbfb8aa3b, v73
	v_mul_f32_e32 v74, 0xbfb8aa3b, v74
	v_mul_f32_e32 v75, 0xbfb8aa3b, v75
	v_mul_f32_e32 v68, 0xbfb8aa3b, v68
	v_mul_f32_e32 v69, 0xbfb8aa3b, v69
	v_mul_f32_e32 v70, 0xbfb8aa3b, v70
	v_mul_f32_e32 v71, 0xbfb8aa3b, v71
	v_exp_f32_e32 v80, v80
	v_exp_f32_e32 v81, v81
	v_exp_f32_e32 v82, v82
	v_exp_f32_e32 v83, v83
	v_exp_f32_e32 v76, v76
	v_exp_f32_e32 v77, v77
	v_exp_f32_e32 v78, v78
	v_exp_f32_e32 v79, v79
	v_exp_f32_e32 v72, v72
	v_exp_f32_e32 v73, v73
	v_exp_f32_e32 v74, v74
	v_exp_f32_e32 v75, v75
	v_exp_f32_e32 v68, v68
	v_exp_f32_e32 v69, v69
; __device__ __forceinline__ unsigned pk2(float lo, float hi) { const f32x2 v = {lo, hi}; return __builtin_bit_cast(unsigned, __builtin_convertvector(v, bf16x2_t)); }
; __device__ __forceinline__ float sigmoidf_(float z) { return __builtin_amdgcn_rcpf(1.0f + __expf(-z)); }
;     __device__ __forceinline__ void operator()(const f32x4 (&acc)[2][2][4][2], const Unit& u, int wr, int wc, int fr, int fq) const {
;     ...
;                     if (P.act == 2) {
;                         if (grp < 4) {
;                             const int bc = col - grp * 512;
;                             const f32x4 c0 = *(const f32x4*)(bias + bc), c1 = *(const f32x4*)(bias + bc + 4);
;                             const float mul = grp < 2 ? -0.60653066f : 1.0f;
; #pragma unroll
;                             for (int j = 0; j < 4; ++j) { v0[j] = mul * sigmoidf_(v0[j] + c0[j]); v1[j] = mul * sigmoidf_(v1[j] + c1[j]); }
;                         } else dst = P.O2 + (size_t)row * 512 + (col - 2048);
;                     }
;                     if (P.ssq) ss += (v0[0] * v0[0] + v0[1] * v0[1]) + (v0[2] * v0[2] + v0[3] * v0[3]) + (v1[0] * v1[0] + v1[1] * v1[1]) + (v1[2] * v1[2] + v1[3] * v1[3]);
;                     if (col < P.ncols) { u32x4 w; w.x = pk2(v0[0], v0[1]); w.y = pk2(v0[2], v0[3]); w.z = pk2(v1[0], v1[1]); w.w = pk2(v1[2], v1[3]);
;                         if (P.ldc >= 3504) __builtin_nontemporal_store(w, (u32x4*)dst); else *(u32x4*)dst = w; }
	v_exp_f32_e32 v70, v70
	v_exp_f32_e32 v71, v71
	v_add_f32_e32 v80, 1.0, v80
	v_add_f32_e32 v81, 1.0, v81
	v_add_f32_e32 v82, 1.0, v82
	v_add_f32_e32 v83, 1.0, v83
	v_add_f32_e32 v76, 1.0, v76
	v_add_f32_e32 v77, 1.0, v77
	v_add_f32_e32 v78, 1.0, v78
	v_add_f32_e32 v79, 1.0, v79
	v_add_f32_e32 v72, 1.0, v72
	v_add_f32_e32 v73, 1.0, v73
	v_add_f32_e32 v74, 1.0, v74
	v_add_f32_e32 v75, 1.0, v75
	v_add_f32_e32 v68, 1.0, v68
	v_add_f32_e32 v69, 1.0, v69
	v_add_f32_e32 v70, 1.0, v70
	v_add_f32_e32 v71, 1.0, v71
	v_rcp_f32_e32 v80, v80
	v_rcp_f32_e32 v81, v81
	v_rcp_f32_e32 v82, v82
	v_rcp_f32_e32 v83, v83
	v_rcp_f32_e32 v76, v76
	v_rcp_f32_e32 v77, v77
	v_rcp_f32_e32 v78, v78
	v_rcp_f32_e32 v79, v79
	v_rcp_f32_e32 v72, v72
	v_rcp_f32_e32 v73, v73
	v_rcp_f32_e32 v74, v74
	v_rcp_f32_e32 v75, v75
	v_rcp_f32_e32 v68, v68
	v_rcp_f32_e32 v69, v69
	v_rcp_f32_e32 v70, v70
	v_rcp_f32_e32 v71, v71
	v_pk_mul_f32 v[76:77], v[158:159], v[76:77] op_sel_hi:[0,1]
	v_pk_mul_f32 v[78:79], v[158:159], v[78:79] op_sel_hi:[0,1]
	v_pk_mul_f32 v[80:81], v[158:159], v[80:81] op_sel_hi:[0,1]
	v_pk_mul_f32 v[82:83], v[158:159], v[82:83] op_sel_hi:[0,1]
	v_pk_mul_f32 v[68:69], v[158:159], v[68:69] op_sel_hi:[0,1]
	v_pk_mul_f32 v[70:71], v[158:159], v[70:71] op_sel_hi:[0,1]
	v_pk_mul_f32 v[72:73], v[158:159], v[72:73] op_sel_hi:[0,1]
	v_pk_mul_f32 v[74:75], v[158:159], v[74:75] op_sel_hi:[0,1]
	v_cvt_pk_bf16_f32 v80, v80, v81
	v_cvt_pk_bf16_f32 v81, v82, v83
	v_cvt_pk_bf16_f32 v82, v76, v77
	v_cvt_pk_bf16_f32 v83, v78, v79
	v_cvt_pk_bf16_f32 v72, v72, v73
	v_cvt_pk_bf16_f32 v73, v74, v75
	v_cvt_pk_bf16_f32 v74, v68, v69
	v_cvt_pk_bf16_f32 v75, v70, v71
	global_store_dwordx4 v153, v[80:83], s[56:57]
	global_store_dwordx4 v153, v[72:75], s[56:57] offset:256
	v_add_f32_e32 v64, v64, v210
	v_add_f32_e32 v65, v65, v211
	v_add_f32_e32 v66, v66, v212
	v_add_f32_e32 v67, v67, v213
	v_add_f32_e32 v60, v60, v214
	v_add_f32_e32 v61, v61, v215
	v_add_f32_e32 v62, v62, v216
	v_add_f32_e32 v63, v63, v217
	v_add_f32_e32 v56, v56, v218
	v_add_f32_e32 v57, v57, v219
	v_add_f32_e32 v58, v58, v220
	v_add_f32_e32 v59, v59, v221
	v_add_f32_e32 v52, v52, v222
	v_add_f32_e32 v53, v53, v223
	v_add_f32_e32 v54, v54, v224
	v_add_f32_e32 v55, v55, v225
	v_mul_f32_e32 v64, 0xbfb8aa3b, v64
	v_mul_f32_e32 v65, 0xbfb8aa3b, v65
	v_mul_f32_e32 v66, 0xbfb8aa3b, v66
	v_mul_f32_e32 v67, 0xbfb8aa3b, v67
	v_mul_f32_e32 v60, 0xbfb8aa3b, v60
	v_mul_f32_e32 v61, 0xbfb8aa3b, v61
	v_mul_f32_e32 v62, 0xbfb8aa3b, v62
	v_mul_f32_e32 v63, 0xbfb8aa3b, v63
	v_mul_f32_e32 v56, 0xbfb8aa3b, v56
	v_mul_f32_e32 v57, 0xbfb8aa3b, v57
	v_mul_f32_e32 v58, 0xbfb8aa3b, v58
	v_mul_f32_e32 v59, 0xbfb8aa3b, v59
	v_mul_f32_e32 v52, 0xbfb8aa3b, v52
	v_mul_f32_e32 v53, 0xbfb8aa3b, v53
	v_mul_f32_e32 v54, 0xbfb8aa3b, v54
	v_mul_f32_e32 v55, 0xbfb8aa3b, v55
	v_exp_f32_e32 v64, v64
	v_exp_f32_e32 v65, v65
	v_exp_f32_e32 v66, v66
	v_exp_f32_e32 v67, v67
	v_exp_f32_e32 v60, v60
	v_exp_f32_e32 v61, v61
	v_exp_f32_e32 v62, v62
	v_exp_f32_e32 v63, v63
	v_exp_f32_e32 v56, v56
	v_exp_f32_e32 v57, v57
	v_exp_f32_e32 v58, v58
	v_exp_f32_e32 v59, v59
	v_exp_f32_e32 v52, v52
	v_exp_f32_e32 v53, v53
	v_exp_f32_e32 v54, v54
	v_exp_f32_e32 v55, v55
	v_add_f32_e32 v64, 1.0, v64
	v_add_f32_e32 v65, 1.0, v65
	v_add_f32_e32 v66, 1.0, v66
	v_add_f32_e32 v67, 1.0, v67
	v_add_f32_e32 v60, 1.0, v60
	v_add_f32_e32 v61, 1.0, v61
	v_add_f32_e32 v62, 1.0, v62
	v_add_f32_e32 v63, 1.0, v63
	v_add_f32_e32 v56, 1.0, v56
	v_add_f32_e32 v57, 1.0, v57
	v_add_f32_e32 v58, 1.0, v58
	v_add_f32_e32 v59, 1.0, v59
	v_add_f32_e32 v52, 1.0, v52
	v_add_f32_e32 v53, 1.0, v53
	v_add_f32_e32 v54, 1.0, v54
	v_add_f32_e32 v55, 1.0, v55
	v_rcp_f32_e32 v64, v64
	v_rcp_f32_e32 v65, v65
	v_rcp_f32_e32 v66, v66
	v_rcp_f32_e32 v67, v67
	v_rcp_f32_e32 v60, v60
	v_rcp_f32_e32 v61, v61
	v_rcp_f32_e32 v62, v62
	v_rcp_f32_e32 v63, v63
	v_rcp_f32_e32 v56, v56
	v_rcp_f32_e32 v57, v57
	v_rcp_f32_e32 v58, v58
	v_rcp_f32_e32 v59, v59
	v_rcp_f32_e32 v52, v52
	v_rcp_f32_e32 v53, v53
	v_rcp_f32_e32 v54, v54
	v_rcp_f32_e32 v55, v55
	v_pk_mul_f32 v[60:61], v[158:159], v[60:61] op_sel_hi:[0,1]
	v_pk_mul_f32 v[62:63], v[158:159], v[62:63] op_sel_hi:[0,1]
	v_pk_mul_f32 v[64:65], v[158:159], v[64:65] op_sel_hi:[0,1]
	v_pk_mul_f32 v[66:67], v[158:159], v[66:67] op_sel_hi:[0,1]
	v_pk_mul_f32 v[52:53], v[158:159], v[52:53] op_sel_hi:[0,1]
	v_pk_mul_f32 v[54:55], v[158:159], v[54:55] op_sel_hi:[0,1]
	v_pk_mul_f32 v[56:57], v[158:159], v[56:57] op_sel_hi:[0,1]
	v_pk_mul_f32 v[58:59], v[158:159], v[58:59] op_sel_hi:[0,1]
	v_cvt_pk_bf16_f32 v64, v64, v65
	v_cvt_pk_bf16_f32 v65, v66, v67
	v_cvt_pk_bf16_f32 v66, v60, v61
	v_cvt_pk_bf16_f32 v67, v62, v63
	v_cvt_pk_bf16_f32 v56, v56, v57
	v_cvt_pk_bf16_f32 v57, v58, v59
	v_cvt_pk_bf16_f32 v58, v52, v53
	v_cvt_pk_bf16_f32 v59, v54, v55
	global_store_dwordx4 v154, v[64:67], s[56:57]
	global_store_dwordx4 v154, v[56:59], s[56:57] offset:256
	v_add_f32_e32 v48, v48, v210
	v_add_f32_e32 v49, v49, v211
	v_add_f32_e32 v50, v50, v212
	v_add_f32_e32 v51, v51, v213
	v_add_f32_e32 v44, v44, v214
	v_add_f32_e32 v45, v45, v215
	v_add_f32_e32 v46, v46, v216
	v_add_f32_e32 v47, v47, v217
	v_add_f32_e32 v40, v40, v218
	v_add_f32_e32 v41, v41, v219
	v_add_f32_e32 v42, v42, v220
	v_add_f32_e32 v43, v43, v221
	v_add_f32_e32 v36, v36, v222
	v_add_f32_e32 v37, v37, v223
	v_add_f32_e32 v38, v38, v224
	v_add_f32_e32 v39, v39, v225
	v_mul_f32_e32 v48, 0xbfb8aa3b, v48
	v_mul_f32_e32 v49, 0xbfb8aa3b, v49
	v_mul_f32_e32 v50, 0xbfb8aa3b, v50
	v_mul_f32_e32 v51, 0xbfb8aa3b, v51
	v_mul_f32_e32 v44, 0xbfb8aa3b, v44
	v_mul_f32_e32 v45, 0xbfb8aa3b, v45
	v_mul_f32_e32 v46, 0xbfb8aa3b, v46
; __device__ __forceinline__ unsigned pk2(float lo, float hi) { const f32x2 v = {lo, hi}; return __builtin_bit_cast(unsigned, __builtin_convertvector(v, bf16x2_t)); }
; __device__ __forceinline__ float sigmoidf_(float z) { return __builtin_amdgcn_rcpf(1.0f + __expf(-z)); }
;     __device__ __forceinline__ void operator()(const f32x4 (&acc)[2][2][4][2], const Unit& u, int wr, int wc, int fr, int fq) const {
;     ...
;                     if (P.act == 2) {
;                         if (grp < 4) {
;                             const int bc = col - grp * 512;
;                             const f32x4 c0 = *(const f32x4*)(bias + bc), c1 = *(const f32x4*)(bias + bc + 4);
;                             const float mul = grp < 2 ? -0.60653066f : 1.0f;
; #pragma unroll
;                             for (int j = 0; j < 4; ++j) { v0[j] = mul * sigmoidf_(v0[j] + c0[j]); v1[j] = mul * sigmoidf_(v1[j] + c1[j]); }
;                         } else dst = P.O2 + (size_t)row * 512 + (col - 2048);
;                     }
;                     if (P.ssq) ss += (v0[0] * v0[0] + v0[1] * v0[1]) + (v0[2] * v0[2] + v0[3] * v0[3]) + (v1[0] * v1[0] + v1[1] * v1[1]) + (v1[2] * v1[2] + v1[3] * v1[3]);
;                     if (col < P.ncols) { u32x4 w; w.x = pk2(v0[0], v0[1]); w.y = pk2(v0[2], v0[3]); w.z = pk2(v1[0], v1[1]); w.w = pk2(v1[2], v1[3]);
;                         if (P.ldc >= 3504) __builtin_nontemporal_store(w, (u32x4*)dst); else *(u32x4*)dst = w; }
	v_mul_f32_e32 v47, 0xbfb8aa3b, v47
	v_mul_f32_e32 v40, 0xbfb8aa3b, v40
	v_mul_f32_e32 v41, 0xbfb8aa3b, v41
	v_mul_f32_e32 v42, 0xbfb8aa3b, v42
	v_mul_f32_e32 v43, 0xbfb8aa3b, v43
	v_mul_f32_e32 v36, 0xbfb8aa3b, v36
	v_mul_f32_e32 v37, 0xbfb8aa3b, v37
	v_mul_f32_e32 v38, 0xbfb8aa3b, v38
	v_mul_f32_e32 v39, 0xbfb8aa3b, v39
	v_exp_f32_e32 v48, v48
	v_exp_f32_e32 v49, v49
	v_exp_f32_e32 v50, v50
	v_exp_f32_e32 v51, v51
	v_exp_f32_e32 v44, v44
	v_exp_f32_e32 v45, v45
	v_exp_f32_e32 v46, v46
	v_exp_f32_e32 v47, v47
	v_exp_f32_e32 v40, v40
	v_exp_f32_e32 v41, v41
	v_exp_f32_e32 v42, v42
	v_exp_f32_e32 v43, v43
	v_exp_f32_e32 v36, v36
	v_exp_f32_e32 v37, v37
	v_exp_f32_e32 v38, v38
	v_exp_f32_e32 v39, v39
	v_add_f32_e32 v48, 1.0, v48
	v_add_f32_e32 v49, 1.0, v49
	v_add_f32_e32 v50, 1.0, v50
	v_add_f32_e32 v51, 1.0, v51
	v_add_f32_e32 v44, 1.0, v44
	v_add_f32_e32 v45, 1.0, v45
	v_add_f32_e32 v46, 1.0, v46
	v_add_f32_e32 v47, 1.0, v47
	v_add_f32_e32 v40, 1.0, v40
	v_add_f32_e32 v41, 1.0, v41
	v_add_f32_e32 v42, 1.0, v42
	v_add_f32_e32 v43, 1.0, v43
	v_add_f32_e32 v36, 1.0, v36
	v_add_f32_e32 v37, 1.0, v37
	v_add_f32_e32 v38, 1.0, v38
	v_add_f32_e32 v39, 1.0, v39
	v_rcp_f32_e32 v48, v48
	v_rcp_f32_e32 v49, v49
	v_rcp_f32_e32 v50, v50
	v_rcp_f32_e32 v51, v51
	v_rcp_f32_e32 v44, v44
	v_rcp_f32_e32 v45, v45
	v_rcp_f32_e32 v46, v46
	v_rcp_f32_e32 v47, v47
	v_rcp_f32_e32 v40, v40
	v_rcp_f32_e32 v41, v41
	v_rcp_f32_e32 v42, v42
	v_rcp_f32_e32 v43, v43
	v_rcp_f32_e32 v36, v36
	v_rcp_f32_e32 v37, v37
	v_rcp_f32_e32 v38, v38
	v_rcp_f32_e32 v39, v39
	v_pk_mul_f32 v[44:45], v[158:159], v[44:45] op_sel_hi:[0,1]
	v_pk_mul_f32 v[46:47], v[158:159], v[46:47] op_sel_hi:[0,1]
	v_pk_mul_f32 v[48:49], v[158:159], v[48:49] op_sel_hi:[0,1]
	v_pk_mul_f32 v[50:51], v[158:159], v[50:51] op_sel_hi:[0,1]
	v_pk_mul_f32 v[36:37], v[158:159], v[36:37] op_sel_hi:[0,1]
	v_pk_mul_f32 v[38:39], v[158:159], v[38:39] op_sel_hi:[0,1]
	v_pk_mul_f32 v[40:41], v[158:159], v[40:41] op_sel_hi:[0,1]
	v_pk_mul_f32 v[42:43], v[158:159], v[42:43] op_sel_hi:[0,1]
	v_cvt_pk_bf16_f32 v48, v48, v49
	v_cvt_pk_bf16_f32 v49, v50, v51
	v_cvt_pk_bf16_f32 v50, v44, v45
	v_cvt_pk_bf16_f32 v51, v46, v47
	v_cvt_pk_bf16_f32 v40, v40, v41
	v_cvt_pk_bf16_f32 v41, v42, v43
	v_cvt_pk_bf16_f32 v42, v36, v37
	v_cvt_pk_bf16_f32 v43, v38, v39
	global_store_dwordx4 v155, v[48:51], s[56:57]
	global_store_dwordx4 v155, v[40:43], s[56:57] offset:256
	v_add_f32_e32 v32, v32, v210
	v_add_f32_e32 v33, v33, v211
	v_add_f32_e32 v34, v34, v212
	v_add_f32_e32 v35, v35, v213
	v_add_f32_e32 v28, v28, v214
	v_add_f32_e32 v29, v29, v215
	v_add_f32_e32 v30, v30, v216
	v_add_f32_e32 v31, v31, v217
	v_add_f32_e32 v24, v24, v218
	v_add_f32_e32 v25, v25, v219
	v_add_f32_e32 v26, v26, v220
	v_add_f32_e32 v27, v27, v221
	v_add_f32_e32 v20, v20, v222
	v_add_f32_e32 v21, v21, v223
	v_add_f32_e32 v22, v22, v224
	v_add_f32_e32 v23, v23, v225
	v_mul_f32_e32 v32, 0xbfb8aa3b, v32
	v_mul_f32_e32 v33, 0xbfb8aa3b, v33
	v_mul_f32_e32 v34, 0xbfb8aa3b, v34
	v_mul_f32_e32 v35, 0xbfb8aa3b, v35
	v_mul_f32_e32 v28, 0xbfb8aa3b, v28
	v_mul_f32_e32 v29, 0xbfb8aa3b, v29
	v_mul_f32_e32 v30, 0xbfb8aa3b, v30
	v_mul_f32_e32 v31, 0xbfb8aa3b, v31
	v_mul_f32_e32 v24, 0xbfb8aa3b, v24
	v_mul_f32_e32 v25, 0xbfb8aa3b, v25
	v_mul_f32_e32 v26, 0xbfb8aa3b, v26
	v_mul_f32_e32 v27, 0xbfb8aa3b, v27
	v_mul_f32_e32 v20, 0xbfb8aa3b, v20
	v_mul_f32_e32 v21, 0xbfb8aa3b, v21
	v_mul_f32_e32 v22, 0xbfb8aa3b, v22
	v_mul_f32_e32 v23, 0xbfb8aa3b, v23
	v_exp_f32_e32 v32, v32
	v_exp_f32_e32 v33, v33
	v_exp_f32_e32 v34, v34
	v_exp_f32_e32 v35, v35
	v_exp_f32_e32 v28, v28
	v_exp_f32_e32 v29, v29
	v_exp_f32_e32 v30, v30
	v_exp_f32_e32 v31, v31
	v_exp_f32_e32 v24, v24
	v_exp_f32_e32 v25, v25
	v_exp_f32_e32 v26, v26
	v_exp_f32_e32 v27, v27
	v_exp_f32_e32 v20, v20
	v_exp_f32_e32 v21, v21
	v_exp_f32_e32 v22, v22
	v_exp_f32_e32 v23, v23
	v_add_f32_e32 v32, 1.0, v32
	v_add_f32_e32 v33, 1.0, v33
	v_add_f32_e32 v34, 1.0, v34
	v_add_f32_e32 v35, 1.0, v35
	v_add_f32_e32 v28, 1.0, v28
	v_add_f32_e32 v29, 1.0, v29
	v_add_f32_e32 v30, 1.0, v30
	v_add_f32_e32 v31, 1.0, v31
	v_add_f32_e32 v24, 1.0, v24
	v_add_f32_e32 v25, 1.0, v25
	v_add_f32_e32 v26, 1.0, v26
	v_add_f32_e32 v27, 1.0, v27
	v_add_f32_e32 v20, 1.0, v20
	v_add_f32_e32 v21, 1.0, v21
	v_add_f32_e32 v22, 1.0, v22
	v_add_f32_e32 v23, 1.0, v23
	v_rcp_f32_e32 v32, v32
	v_rcp_f32_e32 v33, v33
	v_rcp_f32_e32 v34, v34
	v_rcp_f32_e32 v35, v35
	v_rcp_f32_e32 v28, v28
; __device__ __forceinline__ unsigned pk2(float lo, float hi) { const f32x2 v = {lo, hi}; return __builtin_bit_cast(unsigned, __builtin_convertvector(v, bf16x2_t)); }
; __device__ __forceinline__ float sigmoidf_(float z) { return __builtin_amdgcn_rcpf(1.0f + __expf(-z)); }
;     __device__ __forceinline__ void operator()(const f32x4 (&acc)[2][2][4][2], const Unit& u, int wr, int wc, int fr, int fq) const {
;     ...
;                     if (P.act == 2) {
;                         if (grp < 4) {
;                             const int bc = col - grp * 512;
;                             const f32x4 c0 = *(const f32x4*)(bias + bc), c1 = *(const f32x4*)(bias + bc + 4);
;                             const float mul = grp < 2 ? -0.60653066f : 1.0f;
; #pragma unroll
;                             for (int j = 0; j < 4; ++j) { v0[j] = mul * sigmoidf_(v0[j] + c0[j]); v1[j] = mul * sigmoidf_(v1[j] + c1[j]); }
;                         } else dst = P.O2 + (size_t)row * 512 + (col - 2048);
;                     }
;                     if (P.ssq) ss += (v0[0] * v0[0] + v0[1] * v0[1]) + (v0[2] * v0[2] + v0[3] * v0[3]) + (v1[0] * v1[0] + v1[1] * v1[1]) + (v1[2] * v1[2] + v1[3] * v1[3]);
;                     if (col < P.ncols) { u32x4 w; w.x = pk2(v0[0], v0[1]); w.y = pk2(v0[2], v0[3]); w.z = pk2(v1[0], v1[1]); w.w = pk2(v1[2], v1[3]);
;                         if (P.ldc >= 3504) __builtin_nontemporal_store(w, (u32x4*)dst); else *(u32x4*)dst = w; }
	v_rcp_f32_e32 v29, v29
	v_rcp_f32_e32 v30, v30
	v_rcp_f32_e32 v31, v31
	v_rcp_f32_e32 v24, v24
	v_rcp_f32_e32 v25, v25
	v_rcp_f32_e32 v26, v26
	v_rcp_f32_e32 v27, v27
	v_rcp_f32_e32 v20, v20
	v_rcp_f32_e32 v21, v21
	v_rcp_f32_e32 v22, v22
	v_rcp_f32_e32 v23, v23
	v_pk_mul_f32 v[28:29], v[158:159], v[28:29] op_sel_hi:[0,1]
	v_pk_mul_f32 v[30:31], v[158:159], v[30:31] op_sel_hi:[0,1]
	v_pk_mul_f32 v[32:33], v[158:159], v[32:33] op_sel_hi:[0,1]
	v_pk_mul_f32 v[34:35], v[158:159], v[34:35] op_sel_hi:[0,1]
	v_pk_mul_f32 v[20:21], v[158:159], v[20:21] op_sel_hi:[0,1]
	v_pk_mul_f32 v[22:23], v[158:159], v[22:23] op_sel_hi:[0,1]
	v_pk_mul_f32 v[24:25], v[158:159], v[24:25] op_sel_hi:[0,1]
	v_pk_mul_f32 v[26:27], v[158:159], v[26:27] op_sel_hi:[0,1]
	v_cvt_pk_bf16_f32 v32, v32, v33
	v_cvt_pk_bf16_f32 v33, v34, v35
	v_cvt_pk_bf16_f32 v34, v28, v29
	v_cvt_pk_bf16_f32 v35, v30, v31
	v_cvt_pk_bf16_f32 v24, v24, v25
	v_cvt_pk_bf16_f32 v25, v26, v27
	v_cvt_pk_bf16_f32 v26, v20, v21
	v_cvt_pk_bf16_f32 v27, v22, v23
	global_store_dwordx4 v156, v[32:35], s[56:57]
	global_store_dwordx4 v156, v[24:27], s[56:57] offset:256
	v_add_f32_e32 v12, v12, v210
	v_add_f32_e32 v13, v13, v211
	v_add_f32_e32 v14, v14, v212
	v_add_f32_e32 v15, v15, v213
	v_add_f32_e32 v8, v8, v214
	v_add_f32_e32 v9, v9, v215
	v_add_f32_e32 v10, v10, v216
	v_add_f32_e32 v11, v11, v217
	v_add_f32_e32 v4, v4, v218
	v_add_f32_e32 v5, v5, v219
	v_add_f32_e32 v6, v6, v220
	v_add_f32_e32 v7, v7, v221
	v_add_f32_e32 v0, v0, v222
	v_add_f32_e32 v1, v1, v223
	v_add_f32_e32 v2, v2, v224
	v_add_f32_e32 v3, v3, v225
	v_mul_f32_e32 v12, 0xbfb8aa3b, v12
	v_mul_f32_e32 v13, 0xbfb8aa3b, v13
	v_mul_f32_e32 v14, 0xbfb8aa3b, v14
	v_mul_f32_e32 v15, 0xbfb8aa3b, v15
	v_mul_f32_e32 v8, 0xbfb8aa3b, v8
	v_mul_f32_e32 v9, 0xbfb8aa3b, v9
	v_mul_f32_e32 v10, 0xbfb8aa3b, v10
	v_mul_f32_e32 v11, 0xbfb8aa3b, v11
	v_mul_f32_e32 v4, 0xbfb8aa3b, v4
	v_mul_f32_e32 v5, 0xbfb8aa3b, v5
	v_mul_f32_e32 v6, 0xbfb8aa3b, v6
	v_mul_f32_e32 v7, 0xbfb8aa3b, v7
	v_mul_f32_e32 v0, 0xbfb8aa3b, v0
	v_mul_f32_e32 v1, 0xbfb8aa3b, v1
	v_mul_f32_e32 v2, 0xbfb8aa3b, v2
	v_mul_f32_e32 v3, 0xbfb8aa3b, v3
	v_exp_f32_e32 v12, v12
	v_exp_f32_e32 v13, v13
	v_exp_f32_e32 v14, v14
	v_exp_f32_e32 v15, v15
	v_exp_f32_e32 v8, v8
	v_exp_f32_e32 v9, v9
	v_exp_f32_e32 v10, v10
	v_exp_f32_e32 v11, v11
	v_exp_f32_e32 v4, v4
	v_exp_f32_e32 v5, v5
	v_exp_f32_e32 v6, v6
	v_exp_f32_e32 v7, v7
	v_exp_f32_e32 v0, v0
	v_exp_f32_e32 v1, v1
	v_exp_f32_e32 v2, v2
	v_exp_f32_e32 v3, v3
	v_add_f32_e32 v12, 1.0, v12
	v_add_f32_e32 v13, 1.0, v13
	v_add_f32_e32 v14, 1.0, v14
	v_add_f32_e32 v15, 1.0, v15
	v_add_f32_e32 v8, 1.0, v8
	v_add_f32_e32 v9, 1.0, v9
	v_add_f32_e32 v10, 1.0, v10
	v_add_f32_e32 v11, 1.0, v11
	v_add_f32_e32 v4, 1.0, v4
	v_add_f32_e32 v5, 1.0, v5
	v_add_f32_e32 v6, 1.0, v6
	v_add_f32_e32 v7, 1.0, v7
	v_add_f32_e32 v0, 1.0, v0
	v_add_f32_e32 v1, 1.0, v1
	v_add_f32_e32 v2, 1.0, v2
	v_add_f32_e32 v3, 1.0, v3
	v_rcp_f32_e32 v12, v12
	v_rcp_f32_e32 v13, v13
	v_rcp_f32_e32 v14, v14
	v_rcp_f32_e32 v15, v15
	v_rcp_f32_e32 v8, v8
	v_rcp_f32_e32 v9, v9
	v_rcp_f32_e32 v10, v10
	v_rcp_f32_e32 v11, v11
	v_rcp_f32_e32 v4, v4
	v_rcp_f32_e32 v5, v5
	v_rcp_f32_e32 v6, v6
	v_rcp_f32_e32 v7, v7
	v_rcp_f32_e32 v0, v0
	v_rcp_f32_e32 v1, v1
	v_rcp_f32_e32 v2, v2
	v_rcp_f32_e32 v3, v3
	v_pk_mul_f32 v[8:9], v[158:159], v[8:9] op_sel_hi:[0,1]
	v_pk_mul_f32 v[10:11], v[158:159], v[10:11] op_sel_hi:[0,1]
	v_pk_mul_f32 v[12:13], v[158:159], v[12:13] op_sel_hi:[0,1]
	v_pk_mul_f32 v[14:15], v[158:159], v[14:15] op_sel_hi:[0,1]
	v_pk_mul_f32 v[0:1], v[158:159], v[0:1] op_sel_hi:[0,1]
	v_pk_mul_f32 v[2:3], v[158:159], v[2:3] op_sel_hi:[0,1]
	v_pk_mul_f32 v[4:5], v[158:159], v[4:5] op_sel_hi:[0,1]
	v_pk_mul_f32 v[6:7], v[158:159], v[6:7] op_sel_hi:[0,1]
	v_cvt_pk_bf16_f32 v12, v12, v13
	v_cvt_pk_bf16_f32 v13, v14, v15
	v_cvt_pk_bf16_f32 v14, v8, v9
	v_cvt_pk_bf16_f32 v15, v10, v11
	v_cvt_pk_bf16_f32 v4, v4, v5
	v_cvt_pk_bf16_f32 v5, v6, v7
	v_cvt_pk_bf16_f32 v6, v0, v1
	v_cvt_pk_bf16_f32 v7, v2, v3
	global_store_dwordx4 v157, v[12:15], s[56:57]
	global_store_dwordx4 v157, v[4:7], s[56:57] offset:256
	s_branch .LBB0_467
.Lfe_plain:
	v_lshl_add_u32 v144, s70, 8, v190
	v_ashrrev_i32_e32 v145, 31, v144
	v_mov_b32_e32 v202, 1.0
	v_mov_b32_e32 v203, 1.0
	v_mov_b32_e32 v204, 1.0
	v_mov_b32_e32 v205, 1.0
	v_mov_b32_e32 v206, 1.0
	v_mov_b32_e32 v207, 1.0
	v_mov_b32_e32 v208, 1.0
	v_mov_b32_e32 v209, 1.0
	s_branch .Lfe_join

;     __device__ __forceinline__ void operator()(const f32x4 (&acc)[2][2][4][2], const Unit& u, int wr, int wc, int fr, int fq) const {
;     ...
;                 const int row = u.pm * BM + ai * HALF + wr * 64 + m * 16 + fr;
;                 const float rsc = P.rowscale ? P.scal * P.rowscale[row] : P.scal;
;                 float ss = 0.f;
; #pragma unroll
;                 for (int bj = 0; bj < 2; ++bj) {
;                     const int col = colbase + bj * HALF;
;                     f32x4 v0 = acc[ai][bj][m][0] * rsc, v1 = acc[ai][bj][m][1] * rsc;
;                     if (P.colscale) { const f32x4 c0 = *(const f32x4*)(P.colscale + col), c1 = *(const f32x4*)(P.colscale + col + 4); v0 = v0 * c0; v1 = v1 * c1; }
;                     if (P.act == 1) {
; #pragma unroll
;                         for (int j = 0; j < 4; ++j) { const float a0 = v0[j] > 0.f ? v0[j] : 0.f, a1 = v1[j] > 0.f ? v1[j] : 0.f; v0[j] = a0 * a0; v1[j] = a1 * a1; }
;                     }
.Lfe_join:
	v_lshl_or_b32 v146, s7, 8, v192
	v_or_b32_e32 v147, 0x80, v146
	v_cmp_gt_i32_e64 s[18:19], s29, v146
	v_cmp_gt_i32_e64 s[20:21], s29, v147
	v_mul_lo_u32 v150, v144, s58
	v_add_lshl_u32 v150, v150, v146, 1
	s_lshl_b32 s12, s58, 5
	s_mul_i32 s13, s58, 0xa0
	v_add_u32_e32 v151, s12, v150
	v_add_u32_e32 v152, s12, v151
	v_add_u32_e32 v153, s12, v152
	v_add_u32_e32 v154, s13, v153
	v_add_u32_e32 v155, s12, v154
	v_add_u32_e32 v156, s12, v155
	v_add_u32_e32 v157, s12, v156
	s_mov_b64 s[14:15], exec
	s_and_b64 s[18:19], s[14:15], s[18:19]
	s_and_b64 s[20:21], s[14:15], s[20:21]
	s_and_b64 vcc, exec, s[26:27]
	s_waitcnt vmcnt(0)
	v_mul_f32_e32 v158, s44, v202
	v_pk_mul_f32 v[124:125], v[124:125], v[158:159] op_sel_hi:[1,0]
	v_pk_mul_f32 v[126:127], v[126:127], v[158:159] op_sel_hi:[1,0]
	v_pk_mul_f32 v[128:129], v[128:129], v[158:159] op_sel_hi:[1,0]
	v_pk_mul_f32 v[130:131], v[130:131], v[158:159] op_sel_hi:[1,0]
	v_pk_mul_f32 v[116:117], v[116:117], v[158:159] op_sel_hi:[1,0]
	v_pk_mul_f32 v[118:119], v[118:119], v[158:159] op_sel_hi:[1,0]
	v_pk_mul_f32 v[120:121], v[120:121], v[158:159] op_sel_hi:[1,0]
	v_pk_mul_f32 v[122:123], v[122:123], v[158:159] op_sel_hi:[1,0]
	s_cbranch_vccz .Lfe_nr0
	v_max_f32_e32 v124, 0, v124
	v_max_f32_e32 v125, 0, v125
	v_max_f32_e32 v126, 0, v126
	v_max_f32_e32 v127, 0, v127
	v_max_f32_e32 v128, 0, v128
	v_max_f32_e32 v129, 0, v129
	v_max_f32_e32 v130, 0, v130
	v_max_f32_e32 v131, 0, v131
	v_max_f32_e32 v116, 0, v116
	v_max_f32_e32 v117, 0, v117
	v_max_f32_e32 v118, 0, v118
	v_max_f32_e32 v119, 0, v119
	v_max_f32_e32 v120, 0, v120
	v_max_f32_e32 v121, 0, v121
	v_max_f32_e32 v122, 0, v122
	v_max_f32_e32 v123, 0, v123
	v_pk_mul_f32 v[124:125], v[124:125], v[124:125]
	v_pk_mul_f32 v[126:127], v[126:127], v[126:127]
	v_pk_mul_f32 v[128:129], v[128:129], v[128:129]
	v_pk_mul_f32 v[130:131], v[130:131], v[130:131]
	v_pk_mul_f32 v[116:117], v[116:117], v[116:117]
	v_pk_mul_f32 v[118:119], v[118:119], v[118:119]
	v_pk_mul_f32 v[120:121], v[120:121], v[120:121]
	v_pk_mul_f32 v[122:123], v[122:123], v[122:123]
